# grid barrier: last arriver bumps every XCD generation word directly (one release hop less); plus double-tile GEMM B,J
# baseline (speedup 1.0000x reference)
.LBB0_504:
	s_or_b64 exec, exec, s[36:37]
	v_readlane_b32 s26, v253, 49
	v_readlane_b32 s27, v253, 50
	s_orn2_b64 s[36:37], s[38:39], exec
	s_nop 0
	v_mov_b64_e32 v[0:1], s[26:27]
	s_branch .LBB0_505
.Lxb_final:
	s_mov_b64 exec, s[30:31]
	s_sub_u32 s26, s26, 0x1100
	s_subb_u32 s27, s27, 0
	v_mov_b32_e32 v4, 1
	global_atomic_add v129, v4, s[26:27]
	global_atomic_add v129, v4, s[26:27] offset:256
	global_atomic_add v129, v4, s[26:27] offset:512
	global_atomic_add v129, v4, s[26:27] offset:768
	global_atomic_add v129, v4, s[26:27] offset:1024
	global_atomic_add v129, v4, s[26:27] offset:1280
	global_atomic_add v129, v4, s[26:27] offset:1536
	global_atomic_add v129, v4, s[26:27] offset:1792
	global_atomic_add v129, v4, s[26:27] offset:2048
	global_atomic_add v129, v4, s[26:27] offset:2304
	global_atomic_add v129, v4, s[26:27] offset:2560
	global_atomic_add v129, v4, s[26:27] offset:2816
	global_atomic_add v129, v4, s[26:27] offset:3072
	global_atomic_add v129, v4, s[26:27] offset:3328
	global_atomic_add v129, v4, s[26:27] offset:3584
	global_atomic_add v129, v4, s[26:27] offset:3840

.LBB0_507:
	s_or_b64 exec, exec, s[30:31]
	s_mov_b64 s[30:31], exec
	v_mbcnt_lo_u32_b32 v0, s30, 0
	v_mbcnt_hi_u32_b32 v0, s31, v0
	v_cmp_eq_u32_e32 vcc, 0, v0
	s_waitcnt vmcnt(0)
	buffer_inv sc1
	s_and_saveexec_b64 s[36:37], vcc
	s_cbranch_execz .LBB0_509
	s_bcnt1_i32_b64 s25, s[30:31]
	v_readlane_b32 s26, v254, 39
	v_mov_b32_e32 v0, s25
	v_readlane_b32 s27, v254, 40
	s_nop 4
.LBB0_509:
	s_or_b64 exec, exec, s[36:37]
	s_waitcnt vmcnt(0)
